# nt hint on the attention mixer Q / gate row loads (read once)
# baseline (speedup 1.0000x reference)
.LBB0_53:
	s_or_b64 exec, exec, s[6:7]
	s_lshl_b32 s6, s9, 6
	s_or_b32 s6, s6, s28
	v_add_u32_e32 v0, s6, v200
	v_ashrrev_i32_e32 v1, 31, v0
	v_lshlrev_b64 v[0:1], 11, v[0:1]
	v_lshl_or_b32 v4, s8, 9, v96
	v_or_b32_e32 v0, v0, v4
	v_lshl_add_u64 v[2:3], s[12:13], 0, v[0:1]
	v_lshl_add_u64 v[0:1], s[18:19], 0, v[0:1]
	global_load_dwordx4 v[128:131], v[0:1], off nt
	v_add_u32_e32 v0, s6, v201
	v_ashrrev_i32_e32 v1, 31, v0
	v_lshlrev_b64 v[0:1], 11, v[0:1]
	v_or_b32_e32 v0, v0, v4
	global_load_dwordx4 v[124:127], v[2:3], off nt
	v_lshl_add_u64 v[2:3], s[12:13], 0, v[0:1]
	v_lshl_add_u64 v[0:1], s[18:19], 0, v[0:1]
	global_load_dwordx4 v[136:139], v[0:1], off nt
	v_add_u32_e32 v0, s6, v202
	v_ashrrev_i32_e32 v1, 31, v0
	v_lshlrev_b64 v[0:1], 11, v[0:1]
	v_or_b32_e32 v0, v0, v4
	global_load_dwordx4 v[132:135], v[2:3], off nt
	v_lshl_add_u64 v[2:3], s[12:13], 0, v[0:1]
	v_lshl_add_u64 v[0:1], s[18:19], 0, v[0:1]
	global_load_dwordx4 v[144:147], v[0:1], off nt
	v_add_u32_e32 v0, s6, v203
	v_ashrrev_i32_e32 v1, 31, v0
	v_lshlrev_b64 v[0:1], 11, v[0:1]
	v_or_b32_e32 v0, v0, v4
	global_load_dwordx4 v[140:143], v[2:3], off nt
	v_lshl_add_u64 v[2:3], s[12:13], 0, v[0:1]
	v_lshl_add_u64 v[0:1], s[18:19], 0, v[0:1]
	global_load_dwordx4 v[148:151], v[2:3], off nt
	global_load_dwordx4 v[152:155], v[0:1], off nt
